# exact-underflow FoX tile skip (threshold 113+23*Gq*Gk: skipped weights are 0.0 in f32) + direct scalar-column kernel; header states this plainly. NOTE: an earlier validated variant with threshold 48 p
# baseline (speedup 1.0000x reference)
; __device__ __forceinline__ void p5_fox(Frame& F, char* lds) {
;     constexpr int TOTAL = BATCH * NH * (SEQ / 256);
;     __syncthreads();
;     if (F.tid == 0) { const unsigned a_ = __hip_atomic_fetch_add(F.ctl + CW_QUEUE, 1u, RLX_AGENT), b_ = __hip_atomic_fetch_add(F.ctl + CW_QUEUE, 1u, RLX_AGENT); F.MISC[16] = a_; F.MISC[17] = b_; }
;     __syncthreads();
.LBB0_1437:
	s_waitcnt vmcnt(0) lgkmcnt(0)
	s_barrier
	v_mbcnt_lo_u32_b32 v4, -1, 0
	v_mbcnt_hi_u32_b32 v4, -1, v4
	v_readfirstlane_b32 s40, v0
	s_lshr_b32 s40, s40, 6
	v_readlane_b32 s42, v252, 14
	v_readlane_b32 s43, v252, 15
	v_readlane_b32 s44, v252, 16
	v_readlane_b32 s45, v252, 17
	v_lshlrev_b32_e32 v5, 2, v4
	s_nop 4
	global_load_dword v6, v5, s[42:43]
	global_load_dword v7, v5, s[42:43] offset:256
	global_load_dword v8, v5, s[44:45]
	global_load_dword v9, v5, s[44:45] offset:256
	s_waitcnt vmcnt(0)
	v_and_b32_e32 v6, 0x7fffffff, v6
	v_and_b32_e32 v7, 0x7fffffff, v7
	v_and_b32_e32 v8, 0x7fffffff, v8
	v_and_b32_e32 v9, 0x7fffffff, v9
	v_max_u32_e32 v6, v6, v7
	v_max_u32_e32 v8, v8, v9
	v_xor_b32_e32 v10, 4, v5
	ds_bpermute_b32 v11, v10, v6
	ds_bpermute_b32 v12, v10, v8
	s_waitcnt lgkmcnt(0)
	v_max_u32_e32 v6, v6, v11
	v_max_u32_e32 v8, v8, v12
	v_xor_b32_e32 v10, 8, v5
	ds_bpermute_b32 v11, v10, v6
	ds_bpermute_b32 v12, v10, v8
	s_waitcnt lgkmcnt(0)
	v_max_u32_e32 v6, v6, v11
	v_max_u32_e32 v8, v8, v12
	v_xor_b32_e32 v10, 16, v5
	ds_bpermute_b32 v11, v10, v6
	ds_bpermute_b32 v12, v10, v8
	s_waitcnt lgkmcnt(0)
	v_max_u32_e32 v6, v6, v11
	v_max_u32_e32 v8, v8, v12
	v_xor_b32_e32 v10, 32, v5
	ds_bpermute_b32 v11, v10, v6
	ds_bpermute_b32 v12, v10, v8
	s_waitcnt lgkmcnt(0)
	v_max_u32_e32 v6, v6, v11
	v_max_u32_e32 v8, v8, v12
	v_xor_b32_e32 v10, 64, v5
	ds_bpermute_b32 v11, v10, v6
	ds_bpermute_b32 v12, v10, v8
	s_waitcnt lgkmcnt(0)
	v_max_u32_e32 v6, v6, v11
	v_max_u32_e32 v8, v8, v12
	v_xor_b32_e32 v10, 128, v5
	ds_bpermute_b32 v11, v10, v6
	ds_bpermute_b32 v12, v10, v8
	s_waitcnt lgkmcnt(0)
	v_max_u32_e32 v6, v6, v11
	v_max_u32_e32 v8, v8, v12
	v_mul_f32_e32 v6, v6, v8
	v_mov_b32_e32 v7, 0x41b80000
	v_mov_b32_e32 v8, 0x42e20000
	v_fma_f32 v6, v6, v7, v8
	v_mul_f32_e32 v6, 0x41351eb8, v6
	s_add_u32 s46, s82, 0x500000
	s_addc_u32 s47, s83, 0
	v_lshlrev_b32_e32 v9, 6, v4
	v_add_u32_e32 v9, -1, v9
	v_max_i32_e32 v9, 0, v9
	v_lshlrev_b32_e32 v9, 4, v9
	s_lshl_b32 s48, s40, 2
	s_mov_b32 s49, 0
